# P5 down-proj: sample-row tiles split 8-way uneven (12/10 K-tiles) over 128 workgroups instead of 4-way (22) over 64; partials in dead w_in^T region; reduce sums 8
# baseline (speedup 1.0000x reference)
.LBB0_1238:
	s_or_b64 exec, exec, s[2:3]
	s_and_b64 vcc, exec, s[6:7]
	v_readfirstlane_b32 s22, v171
	s_waitcnt lgkmcnt(0)
	s_barrier
	s_cbranch_vccnz .LBB0_1266
	v_readlane_b32 s8, v254, 2
	v_readlane_b32 s9, v254, 3
	v_readlane_b32 s2, v254, 0
	s_nop 0
	s_cmpk_lt_u32 s2, 128
	s_cselect_b32 s3, 0x100, 0
	s_xor_b32 s2, s2, s3
	s_cmpk_lt_i32 s2, 0x100
	s_nop 0
	s_cselect_b32 s2, s2, 0
	s_ashr_i32 s3, s2, 31
	s_lshr_b32 s3, s3, 29
	s_add_i32 s5, s2, s3
	s_and_b32 s3, s5, -8
	s_sub_i32 s4, s2, s3
	s_cmp_gt_i32 s4, -1
	s_cbranch_scc0 .LBB0_1241
	s_lshl_b32 s6, s4, 5
	s_ashr_i32 s2, s5, 3
	s_cbranch_execz .LBB0_1242
	s_branch .LBB0_1243

.LBB0_1243:
	v_readlane_b32 s12, v254, 2
	v_readlane_b32 s13, v254, 3
	s_mov_b64 s[4:5], s[12:13]
	s_add_u32 s23, s4, 0x6600000
	s_addc_u32 s24, s5, 0
	s_add_i32 s2, s6, s2
	s_ashr_i32 s3, s2, 31
	s_lshr_b32 s3, s3, 26
	s_add_i32 s3, s2, s3
	s_ashr_i32 s6, s3, 6
	s_and_b32 s3, s3, 0xffc0
	s_sub_i32 s2, s2, s3
	s_bfe_i32 s3, s2, 0x80000
	s_bfe_u32 s3, s3, 0x3000c
	s_add_i32 s3, s2, s3
	s_bfe_i32 s7, s3, 0x80000
	s_and_b32 s3, s3, 0xf8
	s_sub_i32 s2, s2, s3
	s_lshl_b32 s6, s6, 3
	s_sext_i32_i8 s2, s2
	v_readlane_b32 s11, v254, 0
	s_nop 0
	s_cmpk_lt_u32 s11, 128
	s_cselect_b32 s12, 0x100, 0
	s_xor_b32 s11, s11, s12
	s_add_i32 s6, s6, s2
	s_add_i32 s2, s11, 0xffffff00
	s_lshr_b32 s5, s22, 6
	s_sext_i32_i16 s7, s7
	s_lshr_b32 s2, s2, 6
	s_nop 0
	s_lshr_b32 s4, s22, 8
	s_lshl_b32 s25, s5, 10
	s_ashr_i32 s7, s7, 3
	s_add_i32 s10, s2, 32
	s_cmpk_lt_i32 s11, 0x100
	s_cselect_b64 s[12:13], -1, 0
	s_and_b64 s[2:3], s[12:13], exec
	s_cselect_b32 s50, s6, s10
	s_bfe_u32 s6, s11, 0x30003
	s_and_b64 s[2:3], s[12:13], exec
	s_cselect_b32 s49, s7, s6
	s_and_b32 s2, s11, 7
	s_and_b32 s53, s2, 1
	s_mul_i32 s52, s2, 11
	s_add_i32 s52, s52, s53
	s_lshl_b32 s52, s52, 7
	s_lshl_b32 s53, s53, 1
	s_sub_i32 s53, 12, s53
	s_and_b64 s[6:7], s[12:13], exec
	s_mov_b32 s3, s52
	s_mul_i32 s7, s50, 0x2c0000
	s_cselect_b32 s3, 0, s3
	s_mul_hi_i32 s6, s50, 0x2c0000
	s_add_u32 s7, s0, s7
	s_mul_i32 s10, s49, 0x2c0000
	s_addc_u32 s6, s1, s6
	s_ashr_i32 s11, s10, 31
	s_add_u32 s10, s23, s10
	s_addc_u32 s11, s24, s11
	s_add_u32 s18, s10, s3
	v_mul_u32_u24_e32 v9, 0x2c00, v216
	s_addc_u32 s19, s11, 0
	s_add_i32 s26, s25, 0
	v_or_b32_e32 v140, v9, v215
	s_add_i32 m0, s26, 0x10000
	v_mul_u32_u24_e32 v8, 0x2c00, v217
	global_load_lds_dwordx4 v140, s[18:19]
	s_add_i32 m0, s26, 0x12000
	v_or_b32_e32 v142, v8, v215
	s_add_u32 s16, s7, s3
	global_load_lds_dwordx4 v142, s[18:19]
	s_addc_u32 s17, s6, 0
	s_mov_b32 m0, s26
	s_add_i32 s27, s26, 0x2000
	global_load_lds_dwordx4 v140, s[16:17]
	s_mov_b32 m0, s27
	s_add_u32 s6, s18, 0x160000
	global_load_lds_dwordx4 v142, s[16:17]
	s_addc_u32 s7, s19, 0
	s_add_i32 m0, s26, 0x14000
	v_mov_b32_e32 v145, 0
	global_load_lds_dwordx4 v140, s[6:7]
	s_add_i32 m0, s26, 0x16000
	v_mov_b32_e32 v141, v145
	global_load_lds_dwordx4 v142, s[6:7]
	s_add_u32 s6, s16, 0x160000
	s_addc_u32 s7, s17, 0
	s_add_i32 s28, s26, 0x4000
	s_mov_b32 m0, s28
	s_add_i32 s29, s26, 0x6000
	global_load_lds_dwordx4 v140, s[6:7]
	s_mov_b32 m0, s29
	v_mov_b32_e32 v143, v145
	global_load_lds_dwordx4 v142, s[6:7]
	s_mov_b32 s3, 0
	v_lshl_add_u64 v[6:7], s[18:19], 0, v[140:141]
	v_lshl_add_u64 v[4:5], s[18:19], 0, v[142:143]
	v_lshl_add_u64 v[2:3], s[16:17], 0, v[140:141]
	s_cmp_lg_u32 s4, 1
	v_lshl_add_u64 v[0:1], s[16:17], 0, v[142:143]
	v_readlane_b32 s14, v254, 4
	v_readlane_b32 s15, v254, 5
	s_cbranch_scc1 .LBB0_1245
	s_barrier
.LBB0_1245:
	v_readlane_b32 s6, v254, 0
	s_nop 0
	s_cmpk_gt_u32 s6, 127
	s_mov_b64 s[6:7], 0x80
	s_cselect_b32 s51, 0x58, s53
	s_cselect_b32 s2, -1, s2
	s_lshl_b32 s30, s4, 6
	s_lshl_b32 s10, s4, 13
	s_lshl_b32 s4, s5, 5
	s_add_i32 m0, s26, 0x18000
	v_lshl_add_u64 v[6:7], v[6:7], 0, s[6:7]
	s_and_b32 s31, s4, 0x60
	s_waitcnt vmcnt(4)
	s_barrier
	global_load_lds_dwordx4 v[6:7], off
	v_lshl_add_u64 v[4:5], v[4:5], 0, s[6:7]
	s_add_i32 m0, s26, 0x1a000
	s_add_i32 s33, s26, 0x8000
	s_add_i32 s34, s26, 0xa000
	global_load_lds_dwordx4 v[4:5], off
	v_lshl_add_u64 v[2:3], v[2:3], 0, s[6:7]
	s_mov_b32 m0, s33
	s_add_u32 s4, s18, 0x160080
	global_load_lds_dwordx4 v[2:3], off
	v_lshl_add_u64 v[0:1], v[0:1], 0, s[6:7]
	s_mov_b32 m0, s34
	s_addc_u32 s5, s19, 0
	global_load_lds_dwordx4 v[0:1], off
	s_add_i32 m0, s26, 0x1c000
	v_lshl_add_u64 v[0:1], s[4:5], 0, v[140:141]
	global_load_lds_dwordx4 v[0:1], off
	v_lshl_add_u64 v[0:1], s[4:5], 0, v[142:143]
	s_add_i32 m0, s26, 0x1e000
	v_lshl_or_b32 v158, s31, 7, v214
	global_load_lds_dwordx4 v[0:1], off
	v_lshlrev_b32_e32 v1, 2, v169
	v_lshl_or_b32 v0, v169, 6, v213
	v_and_b32_e32 v1, 32, v1
	s_waitcnt vmcnt(6)
	v_bitop3_b32 v0, v0, s10, v1 bitop3:0xde
	s_add_i32 s35, 0, 0x10000
	s_add_i32 s36, 0, 0x14000
	v_add3_u32 v146, v9, v211, v212
	v_mov_b32_e32 v147, v145
	v_add3_u32 v148, v8, v211, v212
	v_mov_b32_e32 v149, v145
	v_add_u32_e32 v159, s35, v158
	v_add_u32_e32 v160, 0, v0
	v_add_u32_e32 v161, s36, v158
	s_mov_b32 s37, 0x20000
	s_mov_b32 s38, 0x40000
	s_mov_b32 s39, 0x60000
	s_mov_b32 s40, 0x100000
	s_mov_b32 s41, 0x120000
	s_mov_b32 s42, 0x140000
	s_mov_b32 s43, 0x160000
	s_mov_b32 s44, s3
	s_barrier
	s_branch .LBB0_1247

.LBB0_1247:
	s_add_i32 s44, s44, 1
	s_mul_i32 s20, s44, s76
	v_readlane_b32 s4, v254, 0
	s_add_i32 s20, s20, s4
	s_cmpk_lt_u32 s4, 128
	s_cselect_b32 s14, 0x100, 0
	s_xor_b32 s20, s20, s14
	s_cmpk_lt_i32 s20, 0x180
	s_cselect_b64 s[14:15], -1, 0
	s_cmpk_gt_i32 s20, 0x17f
	s_cselect_b64 s[10:11], -1, 0
	s_and_b64 vcc, exec, s[10:11]
	s_cbranch_vccnz .LBB0_1253
	s_cmpk_lt_i32 s20, 0x100
	s_cselect_b64 s[4:5], -1, 0
	s_and_b64 s[12:13], s[4:5], exec
	s_cselect_b32 s12, s20, 0
	s_ashr_i32 s13, s12, 31
	s_lshr_b32 s13, s13, 29
	s_add_i32 s21, s12, s13
	s_and_b32 s13, s21, -8
	s_sub_i32 s45, s12, s13
	s_cmp_gt_i32 s45, -1
	s_mov_b64 s[12:13], -1
	s_cbranch_scc0 .LBB0_1250
	s_lshl_b32 s46, s45, 5
	s_mov_b64 s[12:13], 0

.LBB0_1252:
	s_ashr_i32 s12, s21, 3
	s_add_i32 s12, s46, s12
	s_ashr_i32 s13, s12, 31
	s_lshr_b32 s13, s13, 26
	s_add_i32 s13, s12, s13
	s_ashr_i32 s21, s13, 6
	s_lshl_b32 s21, s21, 3
	s_sub_i32 s45, 32, s21
	s_min_u32 s45, s45, 8
	s_andn2_b32 s13, s13, 63
	s_sub_i32 s46, s12, s13
	v_cvt_f32_ubyte0_e32 v1, s45
	v_cvt_f32_i32_e32 v0, s46
	v_rcp_iflag_f32_e32 v2, v1
	s_ashr_i32 s12, s46, 30
	s_or_b32 s47, s12, 1
	v_mul_f32_e32 v2, v0, v2
	v_trunc_f32_e32 v2, v2
	v_fma_f32 v0, -v2, v1, v0
	v_cvt_i32_f32_e32 v2, v2
	v_cmp_ge_f32_e64 s[12:13], |v0|, v1
	s_and_b64 s[12:13], s[12:13], exec
	s_cselect_b32 s12, s47, 0
	v_readfirstlane_b32 s13, v2
	s_add_i32 s12, s13, s12
	s_sext_i32_i8 s47, s12
	s_mul_i32 s12, s12, s45
	s_sub_i32 s12, s46, s12
	s_sext_i32_i8 s12, s12
	s_add_i32 s21, s21, s12
	s_add_i32 s12, s20, 0xffffff00
	s_ashr_i32 s12, s12, 6
	s_add_i32 s45, s12, 32
	s_and_b64 s[12:13], s[4:5], exec
	s_cselect_b32 s45, s21, s45
	s_bfe_u32 s21, s20, 0x30003
	s_and_b32 s54, s20, 7
	s_and_b32 s55, s54, 1
	s_mul_i32 s54, s54, 11
	s_add_i32 s54, s54, s55
	s_lshl_b32 s55, s55, 1
	s_sub_i32 s55, 12, s55
	s_and_b64 s[12:13], s[4:5], exec
	s_cselect_b32 s47, s47, s21
	s_cselect_b32 s46, 0x58, s55
	s_and_b32 s12, s20, 7
	s_mov_b32 s13, s54
	s_and_b64 s[4:5], s[4:5], exec
	s_cselect_b32 s48, -1, s12
	s_cselect_b32 s12, 0, s13

.LBB0_1330:
	s_or_b64 exec, exec, s[0:1]
	s_mov_b32 s0, 0x40000
	v_cmp_gt_i32_e32 vcc, s0, v168
	s_waitcnt lgkmcnt(0)
	s_barrier
	s_and_saveexec_b64 s[0:1], vcc
	v_readlane_b32 s28, v254, 50
	v_readlane_b32 s29, v254, 51
	s_cbranch_execz .LBB0_1333
	v_readlane_b32 s0, v254, 36
	v_readlane_b32 s1, v254, 37
	v_readlane_b32 s2, v254, 2
	v_readlane_b32 s3, v254, 3
	s_add_u32 s0, s0, 0x4000000
	s_addc_u32 s1, s1, 0
	s_mov_b64 s[10:11], 0
	s_mov_b32 s12, 0x3ffff
.Lp5r_loop:
	v_lshlrev_b32_e32 v48, 4, v168
	s_mov_b64 s[4:5], s[2:3]
	global_load_dwordx4 v[0:3], v48, s[0:1]
	global_load_dwordx4 v[4:7], v48, s[4:5]
	s_add_u32 s4, s4, 0x400000
	s_addc_u32 s5, s5, 0
	global_load_dwordx4 v[8:11], v48, s[4:5]
	s_add_u32 s4, s4, 0x400000
	s_addc_u32 s5, s5, 0
	global_load_dwordx4 v[12:15], v48, s[4:5]
	s_add_u32 s4, s4, 0x400000
	s_addc_u32 s5, s5, 0
	global_load_dwordx4 v[16:19], v48, s[4:5]
	s_add_u32 s4, s4, 0x400000
	s_addc_u32 s5, s5, 0
	global_load_dwordx4 v[20:23], v48, s[4:5]
	s_add_u32 s4, s4, 0x400000
	s_addc_u32 s5, s5, 0
	global_load_dwordx4 v[24:27], v48, s[4:5]
	s_add_u32 s4, s4, 0x400000
	s_addc_u32 s5, s5, 0
	global_load_dwordx4 v[28:31], v48, s[4:5]
	s_add_u32 s4, s4, 0x400000
	s_addc_u32 s5, s5, 0
	global_load_dwordx4 v[32:35], v48, s[4:5]
	v_add_u32_e32 v168, s28, v168
	v_cmp_lt_i32_e32 vcc, s12, v168
	s_or_b64 s[10:11], vcc, s[10:11]
	s_waitcnt vmcnt(0)
	v_pk_add_f32 v[4:5], v[4:5], v[8:9]
	v_pk_add_f32 v[6:7], v[6:7], v[10:11]
	v_pk_add_f32 v[12:13], v[12:13], v[16:17]
	v_pk_add_f32 v[14:15], v[14:15], v[18:19]
	v_pk_add_f32 v[20:21], v[20:21], v[24:25]
	v_pk_add_f32 v[22:23], v[22:23], v[26:27]
	v_pk_add_f32 v[28:29], v[28:29], v[32:33]
	v_pk_add_f32 v[30:31], v[30:31], v[34:35]
	v_pk_add_f32 v[4:5], v[4:5], v[12:13]
	v_pk_add_f32 v[6:7], v[6:7], v[14:15]
	v_pk_add_f32 v[20:21], v[20:21], v[28:29]
	v_pk_add_f32 v[22:23], v[22:23], v[30:31]
	v_pk_add_f32 v[4:5], v[4:5], v[20:21]
	v_pk_add_f32 v[6:7], v[6:7], v[22:23]
	v_pk_add_f32 v[0:1], v[0:1], v[4:5]
	v_pk_add_f32 v[2:3], v[2:3], v[6:7]
	global_store_dwordx4 v48, v[0:3], s[0:1]
	s_andn2_b64 exec, exec, s[10:11]
	s_cbranch_execnz .Lp5r_loop


